# filter MLP output layer: 64 weight loads in flight per wait (same FMA order)
# speedup vs baseline: 1.0335x; 1.0012x over previous
; DEV void phase_filter_mlp(const Params& p, char* smem) {
;     ...
;       for (int k = 0; k < 64; ++k) {
;         float wv[4];
; #pragma unroll
;         for (int q = 0; q < 4; ++q) wv[q] = wo[k * 1024 + tid + 256 * q];
; #pragma unroll
;         for (int a = 0; a < 4; ++a) {
;           const float hv = h3[a * 64 + k];
; #pragma unroll
;           for (int q = 0; q < 4; ++q) acc[a][q] += hv * wv[q];
;         }
;       }
.LBB0_78:
	v_lshl_add_u64 v[62:63], v[26:27], 0, s[0:1]
	v_add_co_u32_e32 v64, vcc, s34, v62
	global_load_dword v78, v[62:63], off
	global_load_dword v79, v[62:63], off offset:1024
	global_load_dword v81, v[62:63], off offset:2048
	global_load_dword v80, v[62:63], off offset:3072
	v_addc_co_u32_e32 v65, vcc, 0, v63, vcc
	v_add_co_u32_e32 v66, vcc, s35, v62
	s_nop 1
	v_addc_co_u32_e32 v67, vcc, 0, v63, vcc
	v_add_co_u32_e32 v62, vcc, s49, v62
	s_nop 1
	v_addc_co_u32_e32 v63, vcc, 0, v63, vcc
	global_load_dword v83, v[64:65], off offset:2048
	global_load_dword v82, v[64:65], off offset:3072
	global_load_dword v85, v[64:65], off offset:1024
	global_load_dword v84, v[66:67], off offset:-4096
	global_load_dword v87, v[66:67], off offset:2048
	global_load_dword v86, v[66:67], off offset:3072
	global_load_dword v88, v[66:67], off
	global_load_dword v89, v[66:67], off offset:1024
	global_load_dword v91, v[62:63], off offset:2048
	global_load_dword v90, v[62:63], off offset:3072
	global_load_dword v92, v[62:63], off
	global_load_dword v93, v[62:63], off offset:1024
	v_lshl_add_u64 v[62:63], v[26:27], 0, s[0:1]
	v_add_co_u32_e32 v62, vcc, 0x4000, v62
	s_nop 0
	v_addc_co_u32_e32 v63, vcc, 0, v63, vcc
	v_add_co_u32_e32 v64, vcc, s34, v62
	global_load_dword v100, v[62:63], off
	global_load_dword v101, v[62:63], off offset:1024
	global_load_dword v103, v[62:63], off offset:2048
	global_load_dword v102, v[62:63], off offset:3072
	v_addc_co_u32_e32 v65, vcc, 0, v63, vcc
	v_add_co_u32_e32 v66, vcc, s35, v62
	s_nop 1
	v_addc_co_u32_e32 v67, vcc, 0, v63, vcc
	v_add_co_u32_e32 v62, vcc, s49, v62
	s_nop 1
	v_addc_co_u32_e32 v63, vcc, 0, v63, vcc
	global_load_dword v105, v[64:65], off offset:2048
	global_load_dword v104, v[64:65], off offset:3072
	global_load_dword v107, v[64:65], off offset:1024
	global_load_dword v106, v[66:67], off offset:-4096
	global_load_dword v109, v[66:67], off offset:2048
	global_load_dword v108, v[66:67], off offset:3072
	global_load_dword v110, v[66:67], off
	global_load_dword v111, v[66:67], off offset:1024
	global_load_dword v113, v[62:63], off offset:2048
	global_load_dword v112, v[62:63], off offset:3072
	global_load_dword v114, v[62:63], off
	global_load_dword v115, v[62:63], off offset:1024
	v_lshl_add_u64 v[62:63], v[26:27], 0, s[0:1]
	v_add_co_u32_e32 v62, vcc, 0x8000, v62
	s_nop 0
	v_addc_co_u32_e32 v63, vcc, 0, v63, vcc
	v_add_co_u32_e32 v64, vcc, s34, v62
	global_load_dword v116, v[62:63], off
	global_load_dword v117, v[62:63], off offset:1024
	global_load_dword v119, v[62:63], off offset:2048
	global_load_dword v118, v[62:63], off offset:3072
	v_addc_co_u32_e32 v65, vcc, 0, v63, vcc
	v_add_co_u32_e32 v66, vcc, s35, v62
	s_nop 1
	v_addc_co_u32_e32 v67, vcc, 0, v63, vcc
	v_add_co_u32_e32 v62, vcc, s49, v62
	s_nop 1
	v_addc_co_u32_e32 v63, vcc, 0, v63, vcc
	global_load_dword v121, v[64:65], off offset:2048
	global_load_dword v120, v[64:65], off offset:3072
	global_load_dword v123, v[64:65], off offset:1024
	global_load_dword v122, v[66:67], off offset:-4096
	global_load_dword v125, v[66:67], off offset:2048
	global_load_dword v124, v[66:67], off offset:3072
	global_load_dword v126, v[66:67], off
	global_load_dword v127, v[66:67], off offset:1024
	global_load_dword v129, v[62:63], off offset:2048
	global_load_dword v128, v[62:63], off offset:3072
	global_load_dword v130, v[62:63], off
	global_load_dword v131, v[62:63], off offset:1024
	v_lshl_add_u64 v[62:63], v[26:27], 0, s[0:1]
	v_add_co_u32_e32 v62, vcc, 0xc000, v62
	s_nop 0
	v_addc_co_u32_e32 v63, vcc, 0, v63, vcc
	v_add_co_u32_e32 v64, vcc, s34, v62
	global_load_dword v132, v[62:63], off
	global_load_dword v133, v[62:63], off offset:1024
	global_load_dword v135, v[62:63], off offset:2048
	global_load_dword v134, v[62:63], off offset:3072
	v_addc_co_u32_e32 v65, vcc, 0, v63, vcc
	v_add_co_u32_e32 v66, vcc, s35, v62
	s_nop 1
	v_addc_co_u32_e32 v67, vcc, 0, v63, vcc
	v_add_co_u32_e32 v62, vcc, s49, v62
	s_nop 1
	v_addc_co_u32_e32 v63, vcc, 0, v63, vcc
	global_load_dword v137, v[64:65], off offset:2048
	global_load_dword v136, v[64:65], off offset:3072
	global_load_dword v139, v[64:65], off offset:1024
	global_load_dword v138, v[66:67], off offset:-4096
	global_load_dword v141, v[66:67], off offset:2048
	global_load_dword v140, v[66:67], off offset:3072
	global_load_dword v142, v[66:67], off
	global_load_dword v143, v[66:67], off offset:1024
	global_load_dword v145, v[62:63], off offset:2048
	global_load_dword v144, v[62:63], off offset:3072
	global_load_dword v146, v[62:63], off
	global_load_dword v147, v[62:63], off offset:1024
	v_mov_b32_e32 v4, s4
	s_add_i32 s4, s4, 16
	ds_read_b128 v[62:65], v4
	ds_read_b128 v[66:69], v4 offset:256
	ds_read_b128 v[70:73], v4 offset:512
	ds_read_b128 v[74:77], v4 offset:768
	s_waitcnt lgkmcnt(3)
	v_mov_b32_e32 v4, v65
	s_waitcnt lgkmcnt(2)
	v_mov_b32_e32 v94, v69
	s_waitcnt lgkmcnt(1)
	v_mov_b32_e32 v96, v73
	s_waitcnt lgkmcnt(0)
	v_mov_b32_e32 v98, v77
	s_waitcnt vmcnt(62)
	v_pk_fma_f32 v[40:41], v[78:79], v[62:63], v[40:41] op_sel_hi:[1,0,1]
	v_pk_fma_f32 v[44:45], v[78:79], v[66:67], v[44:45] op_sel_hi:[1,0,1]
	s_waitcnt vmcnt(60)
	v_pk_fma_f32 v[36:37], v[80:81], v[62:63], v[36:37] op_sel_hi:[1,0,1]
	v_pk_fma_f32 v[34:35], v[80:81], v[66:67], v[34:35] op_sel_hi:[1,0,1]
	v_pk_fma_f32 v[32:33], v[80:81], v[70:71], v[32:33] op_sel_hi:[1,0,1]
	v_pk_fma_f32 v[42:43], v[78:79], v[70:71], v[42:43] op_sel_hi:[1,0,1]
	v_pk_fma_f32 v[38:39], v[78:79], v[74:75], v[38:39] op_sel_hi:[1,0,1]
	v_pk_fma_f32 v[30:31], v[80:81], v[74:75], v[30:31] op_sel_hi:[1,0,1]
	s_waitcnt vmcnt(58)
; DEV void phase_filter_mlp(const Params& p, char* smem) {
;     ...
;       for (int k = 0; k < 64; ++k) {
;         float wv[4];
; #pragma unroll
;         for (int q = 0; q < 4; ++q) wv[q] = wo[k * 1024 + tid + 256 * q];
; #pragma unroll
;         for (int a = 0; a < 4; ++a) {
;           const float hv = h3[a * 64 + k];
; #pragma unroll
;           for (int q = 0; q < 4; ++q) acc[a][q] += hv * wv[q];
;         }
;       }
	v_pk_fma_f32 v[36:37], v[82:83], v[62:63], v[36:37] op_sel:[0,1,0]
	v_pk_fma_f32 v[34:35], v[82:83], v[66:67], v[34:35] op_sel:[0,1,0]
	v_pk_fma_f32 v[32:33], v[82:83], v[70:71], v[32:33] op_sel:[0,1,0]
	s_waitcnt vmcnt(56)
	v_pk_fma_f32 v[40:41], v[84:85], v[62:63], v[40:41] op_sel:[0,1,0]
	v_pk_fma_f32 v[44:45], v[84:85], v[66:67], v[44:45] op_sel:[0,1,0]
	v_pk_fma_f32 v[42:43], v[84:85], v[70:71], v[42:43] op_sel:[0,1,0]
	v_pk_fma_f32 v[38:39], v[84:85], v[74:75], v[38:39] op_sel:[0,1,0]
	v_pk_fma_f32 v[30:31], v[82:83], v[74:75], v[30:31] op_sel:[0,1,0]
	s_waitcnt vmcnt(54)
	v_pk_fma_f32 v[36:37], v[86:87], v[64:65], v[36:37] op_sel_hi:[1,0,1]
	v_pk_fma_f32 v[34:35], v[86:87], v[68:69], v[34:35] op_sel_hi:[1,0,1]
	v_pk_fma_f32 v[32:33], v[86:87], v[72:73], v[32:33] op_sel_hi:[1,0,1]
	s_waitcnt vmcnt(52)
	v_pk_fma_f32 v[40:41], v[88:89], v[64:65], v[40:41] op_sel_hi:[1,0,1]
	v_pk_fma_f32 v[44:45], v[88:89], v[68:69], v[44:45] op_sel_hi:[1,0,1]
	v_pk_fma_f32 v[42:43], v[88:89], v[72:73], v[42:43] op_sel_hi:[1,0,1]
	v_pk_fma_f32 v[38:39], v[88:89], v[76:77], v[38:39] op_sel_hi:[1,0,1]
	v_pk_fma_f32 v[30:31], v[86:87], v[76:77], v[30:31] op_sel_hi:[1,0,1]
	s_waitcnt vmcnt(50)
	v_pk_fma_f32 v[36:37], v[90:91], v[4:5], v[36:37] op_sel_hi:[1,0,1]
	v_pk_fma_f32 v[34:35], v[90:91], v[94:95], v[34:35] op_sel_hi:[1,0,1]
	v_pk_fma_f32 v[32:33], v[90:91], v[96:97], v[32:33] op_sel_hi:[1,0,1]
	s_waitcnt vmcnt(48)
	v_pk_fma_f32 v[40:41], v[92:93], v[4:5], v[40:41] op_sel_hi:[1,0,1]
	v_pk_fma_f32 v[44:45], v[92:93], v[94:95], v[44:45] op_sel_hi:[1,0,1]
	v_pk_fma_f32 v[42:43], v[92:93], v[96:97], v[42:43] op_sel_hi:[1,0,1]
	v_pk_fma_f32 v[38:39], v[92:93], v[98:99], v[38:39] op_sel_hi:[1,0,1]
	v_pk_fma_f32 v[30:31], v[90:91], v[98:99], v[30:31] op_sel_hi:[1,0,1]
	v_mov_b32_e32 v4, s4
	s_add_i32 s4, s4, 16
	ds_read_b128 v[62:65], v4
	ds_read_b128 v[66:69], v4 offset:256
	ds_read_b128 v[70:73], v4 offset:512
	ds_read_b128 v[74:77], v4 offset:768
	s_waitcnt lgkmcnt(3)
	v_mov_b32_e32 v4, v65
	s_waitcnt lgkmcnt(2)
	v_mov_b32_e32 v94, v69
	s_waitcnt lgkmcnt(1)
	v_mov_b32_e32 v96, v73
	s_waitcnt lgkmcnt(0)
	v_mov_b32_e32 v98, v77
	s_waitcnt vmcnt(46)
	v_pk_fma_f32 v[40:41], v[100:101], v[62:63], v[40:41] op_sel_hi:[1,0,1]
	v_pk_fma_f32 v[44:45], v[100:101], v[66:67], v[44:45] op_sel_hi:[1,0,1]
	s_waitcnt vmcnt(44)
	v_pk_fma_f32 v[36:37], v[102:103], v[62:63], v[36:37] op_sel_hi:[1,0,1]
	v_pk_fma_f32 v[34:35], v[102:103], v[66:67], v[34:35] op_sel_hi:[1,0,1]
	v_pk_fma_f32 v[32:33], v[102:103], v[70:71], v[32:33] op_sel_hi:[1,0,1]
	v_pk_fma_f32 v[42:43], v[100:101], v[70:71], v[42:43] op_sel_hi:[1,0,1]
	v_pk_fma_f32 v[38:39], v[100:101], v[74:75], v[38:39] op_sel_hi:[1,0,1]
	v_pk_fma_f32 v[30:31], v[102:103], v[74:75], v[30:31] op_sel_hi:[1,0,1]
	s_waitcnt vmcnt(42)
	v_pk_fma_f32 v[36:37], v[104:105], v[62:63], v[36:37] op_sel:[0,1,0]
	v_pk_fma_f32 v[34:35], v[104:105], v[66:67], v[34:35] op_sel:[0,1,0]
	v_pk_fma_f32 v[32:33], v[104:105], v[70:71], v[32:33] op_sel:[0,1,0]
	s_waitcnt vmcnt(40)
	v_pk_fma_f32 v[40:41], v[106:107], v[62:63], v[40:41] op_sel:[0,1,0]
	v_pk_fma_f32 v[44:45], v[106:107], v[66:67], v[44:45] op_sel:[0,1,0]
	v_pk_fma_f32 v[42:43], v[106:107], v[70:71], v[42:43] op_sel:[0,1,0]
	v_pk_fma_f32 v[38:39], v[106:107], v[74:75], v[38:39] op_sel:[0,1,0]
	v_pk_fma_f32 v[30:31], v[104:105], v[74:75], v[30:31] op_sel:[0,1,0]
	s_waitcnt vmcnt(38)
	v_pk_fma_f32 v[36:37], v[108:109], v[64:65], v[36:37] op_sel_hi:[1,0,1]
	v_pk_fma_f32 v[34:35], v[108:109], v[68:69], v[34:35] op_sel_hi:[1,0,1]
	v_pk_fma_f32 v[32:33], v[108:109], v[72:73], v[32:33] op_sel_hi:[1,0,1]
	s_waitcnt vmcnt(36)
	v_pk_fma_f32 v[40:41], v[110:111], v[64:65], v[40:41] op_sel_hi:[1,0,1]
	v_pk_fma_f32 v[44:45], v[110:111], v[68:69], v[44:45] op_sel_hi:[1,0,1]
	v_pk_fma_f32 v[42:43], v[110:111], v[72:73], v[42:43] op_sel_hi:[1,0,1]
	v_pk_fma_f32 v[38:39], v[110:111], v[76:77], v[38:39] op_sel_hi:[1,0,1]
	v_pk_fma_f32 v[30:31], v[108:109], v[76:77], v[30:31] op_sel_hi:[1,0,1]
	s_waitcnt vmcnt(34)
	v_pk_fma_f32 v[36:37], v[112:113], v[4:5], v[36:37] op_sel_hi:[1,0,1]
	v_pk_fma_f32 v[34:35], v[112:113], v[94:95], v[34:35] op_sel_hi:[1,0,1]
	v_pk_fma_f32 v[32:33], v[112:113], v[96:97], v[32:33] op_sel_hi:[1,0,1]
	s_waitcnt vmcnt(32)
	v_pk_fma_f32 v[40:41], v[114:115], v[4:5], v[40:41] op_sel_hi:[1,0,1]
	v_pk_fma_f32 v[44:45], v[114:115], v[94:95], v[44:45] op_sel_hi:[1,0,1]
	v_pk_fma_f32 v[42:43], v[114:115], v[96:97], v[42:43] op_sel_hi:[1,0,1]
	v_pk_fma_f32 v[38:39], v[114:115], v[98:99], v[38:39] op_sel_hi:[1,0,1]
	v_pk_fma_f32 v[30:31], v[112:113], v[98:99], v[30:31] op_sel_hi:[1,0,1]
	v_mov_b32_e32 v4, s4
	s_add_i32 s4, s4, 16
	ds_read_b128 v[62:65], v4
	ds_read_b128 v[66:69], v4 offset:256
	ds_read_b128 v[70:73], v4 offset:512
	ds_read_b128 v[74:77], v4 offset:768
	s_waitcnt lgkmcnt(3)
	v_mov_b32_e32 v4, v65
	s_waitcnt lgkmcnt(2)
	v_mov_b32_e32 v94, v69
	s_waitcnt lgkmcnt(1)
	v_mov_b32_e32 v96, v73
	s_waitcnt lgkmcnt(0)
	v_mov_b32_e32 v98, v77
	s_waitcnt vmcnt(30)
	v_pk_fma_f32 v[40:41], v[116:117], v[62:63], v[40:41] op_sel_hi:[1,0,1]
	v_pk_fma_f32 v[44:45], v[116:117], v[66:67], v[44:45] op_sel_hi:[1,0,1]
	s_waitcnt vmcnt(28)
	v_pk_fma_f32 v[36:37], v[118:119], v[62:63], v[36:37] op_sel_hi:[1,0,1]
	v_pk_fma_f32 v[34:35], v[118:119], v[66:67], v[34:35] op_sel_hi:[1,0,1]
	v_pk_fma_f32 v[32:33], v[118:119], v[70:71], v[32:33] op_sel_hi:[1,0,1]
	v_pk_fma_f32 v[42:43], v[116:117], v[70:71], v[42:43] op_sel_hi:[1,0,1]
	v_pk_fma_f32 v[38:39], v[116:117], v[74:75], v[38:39] op_sel_hi:[1,0,1]
	v_pk_fma_f32 v[30:31], v[118:119], v[74:75], v[30:31] op_sel_hi:[1,0,1]
	s_waitcnt vmcnt(26)
; DEV void phase_filter_mlp(const Params& p, char* smem) {
;     ...
;       for (int k = 0; k < 64; ++k) {
;         float wv[4];
; #pragma unroll
;         for (int q = 0; q < 4; ++q) wv[q] = wo[k * 1024 + tid + 256 * q];
; #pragma unroll
;         for (int a = 0; a < 4; ++a) {
;           const float hv = h3[a * 64 + k];
; #pragma unroll
;           for (int q = 0; q < 4; ++q) acc[a][q] += hv * wv[q];
;         }
;       }
	v_pk_fma_f32 v[36:37], v[120:121], v[62:63], v[36:37] op_sel:[0,1,0]
	v_pk_fma_f32 v[34:35], v[120:121], v[66:67], v[34:35] op_sel:[0,1,0]
	v_pk_fma_f32 v[32:33], v[120:121], v[70:71], v[32:33] op_sel:[0,1,0]
	s_waitcnt vmcnt(24)
	v_pk_fma_f32 v[40:41], v[122:123], v[62:63], v[40:41] op_sel:[0,1,0]
	v_pk_fma_f32 v[44:45], v[122:123], v[66:67], v[44:45] op_sel:[0,1,0]
	v_pk_fma_f32 v[42:43], v[122:123], v[70:71], v[42:43] op_sel:[0,1,0]
	v_pk_fma_f32 v[38:39], v[122:123], v[74:75], v[38:39] op_sel:[0,1,0]
	v_pk_fma_f32 v[30:31], v[120:121], v[74:75], v[30:31] op_sel:[0,1,0]
	s_waitcnt vmcnt(22)
	v_pk_fma_f32 v[36:37], v[124:125], v[64:65], v[36:37] op_sel_hi:[1,0,1]
	v_pk_fma_f32 v[34:35], v[124:125], v[68:69], v[34:35] op_sel_hi:[1,0,1]
	v_pk_fma_f32 v[32:33], v[124:125], v[72:73], v[32:33] op_sel_hi:[1,0,1]
	s_waitcnt vmcnt(20)
	v_pk_fma_f32 v[40:41], v[126:127], v[64:65], v[40:41] op_sel_hi:[1,0,1]
	v_pk_fma_f32 v[44:45], v[126:127], v[68:69], v[44:45] op_sel_hi:[1,0,1]
	v_pk_fma_f32 v[42:43], v[126:127], v[72:73], v[42:43] op_sel_hi:[1,0,1]
	v_pk_fma_f32 v[38:39], v[126:127], v[76:77], v[38:39] op_sel_hi:[1,0,1]
	v_pk_fma_f32 v[30:31], v[124:125], v[76:77], v[30:31] op_sel_hi:[1,0,1]
	s_waitcnt vmcnt(18)
	v_pk_fma_f32 v[36:37], v[128:129], v[4:5], v[36:37] op_sel_hi:[1,0,1]
	v_pk_fma_f32 v[34:35], v[128:129], v[94:95], v[34:35] op_sel_hi:[1,0,1]
	v_pk_fma_f32 v[32:33], v[128:129], v[96:97], v[32:33] op_sel_hi:[1,0,1]
	s_waitcnt vmcnt(16)
	v_pk_fma_f32 v[40:41], v[130:131], v[4:5], v[40:41] op_sel_hi:[1,0,1]
	v_pk_fma_f32 v[44:45], v[130:131], v[94:95], v[44:45] op_sel_hi:[1,0,1]
	v_pk_fma_f32 v[42:43], v[130:131], v[96:97], v[42:43] op_sel_hi:[1,0,1]
	v_pk_fma_f32 v[38:39], v[130:131], v[98:99], v[38:39] op_sel_hi:[1,0,1]
	v_pk_fma_f32 v[30:31], v[128:129], v[98:99], v[30:31] op_sel_hi:[1,0,1]
	v_mov_b32_e32 v4, s4
	s_add_i32 s4, s4, 16
	ds_read_b128 v[62:65], v4
	ds_read_b128 v[66:69], v4 offset:256
	ds_read_b128 v[70:73], v4 offset:512
	ds_read_b128 v[74:77], v4 offset:768
	s_waitcnt lgkmcnt(3)
	v_mov_b32_e32 v4, v65
	s_waitcnt lgkmcnt(2)
	v_mov_b32_e32 v94, v69
	s_waitcnt lgkmcnt(1)
	v_mov_b32_e32 v96, v73
	s_waitcnt lgkmcnt(0)
	v_mov_b32_e32 v98, v77
	s_waitcnt vmcnt(14)
	v_pk_fma_f32 v[40:41], v[132:133], v[62:63], v[40:41] op_sel_hi:[1,0,1]
	v_pk_fma_f32 v[44:45], v[132:133], v[66:67], v[44:45] op_sel_hi:[1,0,1]
	s_waitcnt vmcnt(12)
	v_pk_fma_f32 v[36:37], v[134:135], v[62:63], v[36:37] op_sel_hi:[1,0,1]
	v_pk_fma_f32 v[34:35], v[134:135], v[66:67], v[34:35] op_sel_hi:[1,0,1]
	v_pk_fma_f32 v[32:33], v[134:135], v[70:71], v[32:33] op_sel_hi:[1,0,1]
	v_pk_fma_f32 v[42:43], v[132:133], v[70:71], v[42:43] op_sel_hi:[1,0,1]
	v_pk_fma_f32 v[38:39], v[132:133], v[74:75], v[38:39] op_sel_hi:[1,0,1]
	v_pk_fma_f32 v[30:31], v[134:135], v[74:75], v[30:31] op_sel_hi:[1,0,1]
	s_waitcnt vmcnt(10)
	v_pk_fma_f32 v[36:37], v[136:137], v[62:63], v[36:37] op_sel:[0,1,0]
	v_pk_fma_f32 v[34:35], v[136:137], v[66:67], v[34:35] op_sel:[0,1,0]
	v_pk_fma_f32 v[32:33], v[136:137], v[70:71], v[32:33] op_sel:[0,1,0]
	s_waitcnt vmcnt(8)
	v_pk_fma_f32 v[40:41], v[138:139], v[62:63], v[40:41] op_sel:[0,1,0]
	v_pk_fma_f32 v[44:45], v[138:139], v[66:67], v[44:45] op_sel:[0,1,0]
	v_pk_fma_f32 v[42:43], v[138:139], v[70:71], v[42:43] op_sel:[0,1,0]
	v_pk_fma_f32 v[38:39], v[138:139], v[74:75], v[38:39] op_sel:[0,1,0]
	v_pk_fma_f32 v[30:31], v[136:137], v[74:75], v[30:31] op_sel:[0,1,0]
	s_waitcnt vmcnt(6)
	v_pk_fma_f32 v[36:37], v[140:141], v[64:65], v[36:37] op_sel_hi:[1,0,1]
	v_pk_fma_f32 v[34:35], v[140:141], v[68:69], v[34:35] op_sel_hi:[1,0,1]
	v_pk_fma_f32 v[32:33], v[140:141], v[72:73], v[32:33] op_sel_hi:[1,0,1]
	s_waitcnt vmcnt(4)
	v_pk_fma_f32 v[40:41], v[142:143], v[64:65], v[40:41] op_sel_hi:[1,0,1]
	v_pk_fma_f32 v[44:45], v[142:143], v[68:69], v[44:45] op_sel_hi:[1,0,1]
	v_pk_fma_f32 v[42:43], v[142:143], v[72:73], v[42:43] op_sel_hi:[1,0,1]
	v_pk_fma_f32 v[38:39], v[142:143], v[76:77], v[38:39] op_sel_hi:[1,0,1]
	v_pk_fma_f32 v[30:31], v[140:141], v[76:77], v[30:31] op_sel_hi:[1,0,1]
	s_waitcnt vmcnt(2)
	v_pk_fma_f32 v[36:37], v[144:145], v[4:5], v[36:37] op_sel_hi:[1,0,1]
	v_pk_fma_f32 v[34:35], v[144:145], v[94:95], v[34:35] op_sel_hi:[1,0,1]
	v_pk_fma_f32 v[32:33], v[144:145], v[96:97], v[32:33] op_sel_hi:[1,0,1]
	s_waitcnt vmcnt(0)
	v_pk_fma_f32 v[40:41], v[146:147], v[4:5], v[40:41] op_sel_hi:[1,0,1]
	v_pk_fma_f32 v[44:45], v[146:147], v[94:95], v[44:45] op_sel_hi:[1,0,1]
	v_pk_fma_f32 v[42:43], v[146:147], v[96:97], v[42:43] op_sel_hi:[1,0,1]
	v_pk_fma_f32 v[38:39], v[146:147], v[98:99], v[38:39] op_sel_hi:[1,0,1]
	v_pk_fma_f32 v[30:31], v[144:145], v[98:99], v[30:31] op_sel_hi:[1,0,1]
	s_add_u32 s0, s0, 0x10000
	s_addc_u32 s1, s1, 0
	s_cmp_eq_u32 s0, 0x40000
	s_cbranch_scc0 .LBB0_78
; DEV void phase_filter_mlp(const Params& p, char* smem) {
;     ...
; #pragma unroll
;       for (int q = 0; q < 4; ++q) {
;         const int c = tid + 256 * q;
;         const int ch = c & 511;
;         const float mind = -3.0701134573253943f, maxd = -15.350567286626972f;
;         const float delta = fabsf(mind + (float)ch * ((maxd - mind) / 511.0f));
; #pragma unroll
;         for (int a = 0; a < 4; ++a) {
;           const int t = t0 + a;
;           const float tt = (float)t / (float)(L - 1);
;           const float val = acc[a][q] * __expf(-tt * delta);
;           hraw[(rowbase + t) * 1024 + c] = val;
;           if (!(c >= 512 && t == 0)) psum[q] += fabsf(val);
;         }
;       }
	v_cvt_f32_i32_e32 v4, s53
	s_ashr_i32 s4, s53, 31
	v_div_scale_f32 v62, s[0:1], v59, v59, -v4
	v_rcp_f32_e32 v63, v62
	v_div_scale_f32 v64, vcc, -v4, v59, -v4
	s_add_u32 s0, s51, s53
	v_fma_f32 v65, -v62, v63, 1.0
	v_fmac_f32_e32 v63, v65, v63
	v_mul_f32_e32 v65, v64, v63
	v_fma_f32 v66, -v62, v65, v64
	v_fmac_f32_e32 v65, v66, v63
	v_fma_f32 v62, -v62, v65, v64
	s_addc_u32 s1, 0, s4
	s_or_b32 s8, s53, 1
	v_div_fmas_f32 v62, v62, v63, v65
	v_cvt_f32_i32_e32 v63, s8
	s_lshl_b64 s[0:1], s[0:1], 12
	v_div_fixup_f32 v4, v62, v59, -v4
	v_mul_f32_e64 v62, |v49|, v4
	v_div_scale_f32 v66, s[4:5], v59, v59, -v63
	v_rcp_f32_e32 v67, v66
	s_ashr_i32 s5, s8, 31
	s_add_u32 s4, s51, s8
	s_addc_u32 s5, 0, s5
	v_fma_f32 v68, -v66, v67, 1.0
	v_fmac_f32_e32 v67, v68, v67
	v_div_scale_f32 v68, vcc, -v63, v59, -v63
	v_mul_f32_e32 v69, v68, v67
	v_fma_f32 v70, -v66, v69, v68
	v_fmac_f32_e32 v69, v70, v67
	v_fma_f32 v66, -v66, v69, v68
	v_div_fmas_f32 v66, v66, v67, v69
	s_or_b32 s20, s53, 2
	v_div_fixup_f32 v67, v66, v59, -v63
	v_cvt_f32_i32_e32 v63, s20
	s_lshl_b64 s[4:5], s[4:5], 12
	v_mul_f32_e64 v4, |v48|, v4
	v_mul_f32_e32 v4, 0x3fb8aa3b, v4
	v_div_scale_f32 v70, s[8:9], v59, v59, -v63
	v_rcp_f32_e32 v71, v70
	s_ashr_i32 s9, s20, 31
	s_add_u32 s8, s51, s20
	s_addc_u32 s9, 0, s9
	v_fma_f32 v72, -v70, v71, 1.0
	v_fmac_f32_e32 v71, v72, v71
	v_div_scale_f32 v72, vcc, -v63, v59, -v63
	v_mul_f32_e32 v73, v72, v71
	v_fma_f32 v74, -v70, v73, v72
	v_fmac_f32_e32 v73, v74, v71
	v_fma_f32 v70, -v70, v73, v72
	v_div_fmas_f32 v70, v70, v71, v73
	s_or_b32 s22, s53, 3
	v_div_fixup_f32 v71, v70, v59, -v63
	v_cvt_f32_i32_e32 v63, s22
	v_mul_f32_e64 v66, |v49|, v67
	v_mul_f32_e64 v70, |v49|, v71
	v_mul_f32_e32 v62, 0x3fb8aa3b, v62
	v_div_scale_f32 v74, s[20:21], v59, v59, -v63
	v_rcp_f32_e32 v75, v74
	v_mul_f32_e32 v66, 0x3fb8aa3b, v66
	v_mul_f32_e32 v70, 0x3fb8aa3b, v70
	v_exp_f32_e32 v62, v62
	v_fma_f32 v76, -v74, v75, 1.0
	v_fmac_f32_e32 v75, v76, v75
	v_div_scale_f32 v76, vcc, -v63, v59, -v63
	v_mul_f32_e32 v77, v76, v75
	v_fma_f32 v78, -v74, v77, v76
	v_fmac_f32_e32 v77, v78, v75
	v_fma_f32 v74, -v74, v77, v76
	v_div_fmas_f32 v74, v74, v75, v77
	v_div_fixup_f32 v75, v74, v59, -v63
	v_mul_f32_e64 v63, |v49|, v75
	v_mul_f32_e32 v63, 0x3fb8aa3b, v63
	v_exp_f32_e32 v74, v63
	v_exp_f32_e32 v63, v4
	v_mul_f32_e64 v4, |v48|, v67
	v_mul_f32_e32 v4, 0x3fb8aa3b, v4
	v_exp_f32_e32 v67, v4
	v_mul_f32_e64 v4, |v48|, v71
	v_mul_f32_e32 v4, 0x3fb8aa3b, v4
	v_exp_f32_e32 v71, v4
	v_mul_f32_e64 v4, |v48|, v75
	v_mul_f32_e32 v4, 0x3fb8aa3b, v4
	v_exp_f32_e32 v66, v66
	v_exp_f32_e32 v70, v70
	s_lshl_b64 s[8:9], s[8:9], 12
	s_ashr_i32 s21, s22, 31
	v_exp_f32_e32 v75, v4
	s_add_u32 s20, s51, s22
	s_addc_u32 s21, 0, s21
	s_lshl_b64 s[20:21], s[20:21], 12
	v_lshl_add_u64 v[64:65], v[16:17], 0, s[0:1]
	v_lshl_add_u64 v[68:69], v[16:17], 0, s[4:5]
	v_lshl_add_u64 v[72:73], v[16:17], 0, s[8:9]
	v_lshl_add_u64 v[76:77], v[16:17], 0, s[20:21]
	v_lshl_add_u64 v[78:79], v[18:19], 0, s[0:1]
	v_pk_mul_f32 v[40:41], v[62:63], v[40:41]
	v_pk_mul_f32 v[44:45], v[66:67], v[44:45]
	v_pk_mul_f32 v[42:43], v[70:71], v[42:43]
	v_pk_mul_f32 v[38:39], v[74:75], v[38:39]
	v_mul_f32_e32 v4, v62, v37
	s_cmp_eq_u32 s53, 0
	v_lshl_add_u64 v[80:81], v[18:19], 0, s[4:5]
	v_lshl_add_u64 v[82:83], v[18:19], 0, s[8:9]
	v_lshl_add_u64 v[84:85], v[18:19], 0, s[20:21]
	global_store_dword v[64:65], v40, off
	global_store_dword v[68:69], v44, off
	global_store_dword v[72:73], v42, off
	global_store_dword v[76:77], v38, off
	global_store_dword v[78:79], v41, off
	global_store_dword v[80:81], v45, off
	global_store_dword v[82:83], v43, off
	global_store_dword v[84:85], v39, off
	global_store_dword v[64:65], v4, off offset:2048
	v_add_f32_e64 v4, v61, |v4|
	s_cselect_b64 vcc, -1, 0
	v_cndmask_b32_e32 v4, v4, v61, vcc
	v_mul_f32_e32 v35, v66, v35
	v_add_f32_e64 v4, |v35|, v4
	v_mul_f32_e32 v33, v70, v33
	v_add_f32_e64 v4, |v33|, v4
	v_mul_f32_e32 v31, v74, v31
	v_and_b32_e32 v87, 0x7fffffff, v41
	v_and_b32_e32 v86, 0x7fffffff, v40
	v_cndmask_b32_e32 v3, v3, v3, vcc
	v_add_f32_e64 v61, |v31|, v4
	v_mul_f32_e32 v4, v63, v36
	v_pk_add_f32 v[28:29], v[28:29], v[86:87]
	v_and_b32_e32 v87, 0x7fffffff, v45
	v_and_b32_e32 v86, 0x7fffffff, v44
	global_store_dword v[64:65], v4, off offset:3072
	v_add_f32_e64 v4, |v4|, v3
	v_pk_add_f32 v[28:29], v[28:29], v[86:87]
	v_and_b32_e32 v87, 0x7fffffff, v43
	v_and_b32_e32 v86, 0x7fffffff, v42
	v_cndmask_b32_e32 v3, v4, v3, vcc
	v_mul_f32_e32 v4, v67, v34
	v_pk_add_f32 v[28:29], v[28:29], v[86:87]
	v_and_b32_e32 v87, 0x7fffffff, v39
	v_and_b32_e32 v86, 0x7fffffff, v38
	global_store_dword v[68:69], v4, off offset:3072
	v_add_f32_e64 v3, |v4|, v3
	v_mul_f32_e32 v4, v71, v32
	v_pk_add_f32 v[28:29], v[28:29], v[86:87]
	global_store_dword v[72:73], v4, off offset:3072
	v_add_f32_e64 v3, |v4|, v3
	v_mul_f32_e32 v4, v75, v30
	s_add_i32 s52, s52, 1
	v_cndmask_b32_e32 v29, v29, v29, vcc
	v_cndmask_b32_e32 v28, v28, v28, vcc
	s_cmp_eq_u32 s52, 4
	v_add_f32_e64 v3, |v4|, v3
	global_store_dword v[68:69], v35, off offset:2048
	global_store_dword v[72:73], v33, off offset:2048
	global_store_dword v[76:77], v31, off offset:2048
	global_store_dword v[76:77], v4, off offset:3072
	s_cbranch_scc0 .LBB0_42
	s_branch .LBB0_40
